# gdn local-term pass also uses factored scalar decay (S=A*U) with rare-path rescale; on top of transition pass
# baseline (speedup 1.0000x reference)
; template <int MODE>
; __device__ __forceinline__ void gdn_job(const Params& P, float* lw, int head, int rb, int seg) {
;     ...
;     u32x4 g_k0, g_k1, g_q0, g_q1; u32x2 g_v; float g_al = 0.f, g_be = 0.f;
;     const int tbase = seg * SEGLEN;
;     auto issue = [&](int blk) {
;         const int t = tbase + blk * TBK + ltt;
;         const bf16_t* rowp = gp + (size_t)t * 2048;
;         g_k0 = *(const u32x4*)(rowp + 512 + qh * 128 + lc16); g_k1 = *(const u32x4*)(rowp + 512 + qh * 128 + lc16 + 8);
;         if (MODE == 2) { g_q0 = *(const u32x4*)(rowp + qh * 128 + lc16); g_q1 = *(const u32x4*)(rowp + qh * 128 + lc16 + 8); }
;         if (MODE != 0) g_v = *(const u32x2*)(rowp + 1024 + head * 128 + rb * 32 + lc4);
;         if (lane < TBK) { const int tq = tbase + blk * TBK + lane; g_al = gg[tq * 8 + head]; g_be = gbeta[tq * 8 + head]; }
;     };
;     issue(0);
;     ...
;     if (MODE != 2) {
;         float* dp = (float*)((unsigned char*)P.out + (MODE == 0 ? 64 * MiB : 96 * MiB)) + ((size_t)(head * NSEG + seg) * 128 + row0) * 128 + jg * 16;
; #pragma unroll
;         for (int ri = 0; ri < 4; ++ri)
; #pragma unroll
;             for (int q4 = 0; q4 < 4; ++q4) *(f32x4*)(dp + ri * 128 + q4 * 4) = (f32x4){S[ri][2 * q4].x, S[ri][2 * q4].y, S[ri][2 * q4 + 1].x, S[ri][2 * q4 + 1].y};
;     }
.LBB0_498:
	v_pk_mul_f32 v[70:71], v[70:71], v[236:237] op_sel_hi:[1,0]
	v_pk_mul_f32 v[72:73], v[72:73], v[236:237] op_sel_hi:[1,0]
	v_pk_mul_f32 v[66:67], v[66:67], v[236:237] op_sel_hi:[1,0]
	v_pk_mul_f32 v[68:69], v[68:69], v[236:237] op_sel_hi:[1,0]
	v_pk_mul_f32 v[62:63], v[62:63], v[236:237] op_sel_hi:[1,0]
	v_pk_mul_f32 v[64:65], v[64:65], v[236:237] op_sel_hi:[1,0]
	v_pk_mul_f32 v[58:59], v[58:59], v[236:237] op_sel_hi:[1,0]
	v_pk_mul_f32 v[60:61], v[60:61], v[236:237] op_sel_hi:[1,0]
	v_pk_mul_f32 v[54:55], v[54:55], v[236:237] op_sel_hi:[1,0]
	v_pk_mul_f32 v[56:57], v[56:57], v[236:237] op_sel_hi:[1,0]
	v_pk_mul_f32 v[50:51], v[50:51], v[236:237] op_sel_hi:[1,0]
	v_pk_mul_f32 v[52:53], v[52:53], v[236:237] op_sel_hi:[1,0]
	v_pk_mul_f32 v[46:47], v[46:47], v[236:237] op_sel_hi:[1,0]
	v_pk_mul_f32 v[48:49], v[48:49], v[236:237] op_sel_hi:[1,0]
	v_pk_mul_f32 v[42:43], v[42:43], v[236:237] op_sel_hi:[1,0]
	v_pk_mul_f32 v[44:45], v[44:45], v[236:237] op_sel_hi:[1,0]
	v_pk_mul_f32 v[38:39], v[38:39], v[236:237] op_sel_hi:[1,0]
	v_pk_mul_f32 v[40:41], v[40:41], v[236:237] op_sel_hi:[1,0]
	v_pk_mul_f32 v[26:27], v[26:27], v[236:237] op_sel_hi:[1,0]
	v_pk_mul_f32 v[28:29], v[28:29], v[236:237] op_sel_hi:[1,0]
	v_pk_mul_f32 v[18:19], v[18:19], v[236:237] op_sel_hi:[1,0]
	v_pk_mul_f32 v[20:21], v[20:21], v[236:237] op_sel_hi:[1,0]
	v_pk_mul_f32 v[10:11], v[10:11], v[236:237] op_sel_hi:[1,0]
	v_pk_mul_f32 v[12:13], v[12:13], v[236:237] op_sel_hi:[1,0]
	v_pk_mul_f32 v[34:35], v[34:35], v[236:237] op_sel_hi:[1,0]
	v_pk_mul_f32 v[36:37], v[36:37], v[236:237] op_sel_hi:[1,0]
	v_pk_mul_f32 v[30:31], v[30:31], v[236:237] op_sel_hi:[1,0]
	v_pk_mul_f32 v[32:33], v[32:33], v[236:237] op_sel_hi:[1,0]
	v_pk_mul_f32 v[22:23], v[22:23], v[236:237] op_sel_hi:[1,0]
	v_pk_mul_f32 v[24:25], v[24:25], v[236:237] op_sel_hi:[1,0]
	v_pk_mul_f32 v[14:15], v[14:15], v[236:237] op_sel_hi:[1,0]
	v_pk_mul_f32 v[16:17], v[16:17], v[236:237] op_sel_hi:[1,0]
	s_waitcnt vmcnt(2)
	v_or_b32_e32 v2, v149, v113
	v_ashrrev_i32_e32 v3, 31, v2
	v_or_b32_e32 v4, v147, v138
	v_lshlrev_b64 v[2:3], 16, v[2:3]
	v_lshl_add_u64 v[2:3], s[18:19], 0, v[2:3]
	v_lshlrev_b32_e32 v116, 9, v4
	v_add_u32_e32 v145, s42, v145
	v_lshl_add_u64 v[2:3], v[2:3], 0, v[116:117]
	v_mov_b32_e32 v113, v117
	v_cmp_lt_i32_e64 s[6:7], s40, v145
	v_lshl_add_u64 v[2:3], v[2:3], 0, v[112:113]
	s_or_b64 s[56:57], s[6:7], s[56:57]
	global_store_dwordx4 v[2:3], v[70:73], off
	global_store_dwordx4 v[2:3], v[66:69], off offset:16
	global_store_dwordx4 v[2:3], v[62:65], off offset:32
	global_store_dwordx4 v[2:3], v[58:61], off offset:48
	global_store_dwordx4 v[2:3], v[54:57], off offset:512
	global_store_dwordx4 v[2:3], v[50:53], off offset:528
	global_store_dwordx4 v[2:3], v[46:49], off offset:544
	global_store_dwordx4 v[2:3], v[42:45], off offset:560
	global_store_dwordx4 v[2:3], v[38:41], off offset:1024
	global_store_dwordx4 v[2:3], v[26:29], off offset:1040
	global_store_dwordx4 v[2:3], v[18:21], off offset:1056
	global_store_dwordx4 v[2:3], v[10:13], off offset:1072
	global_store_dwordx4 v[2:3], v[34:37], off offset:1536
	global_store_dwordx4 v[2:3], v[30:33], off offset:1552
	global_store_dwordx4 v[2:3], v[22:25], off offset:1568
	global_store_dwordx4 v[2:3], v[14:17], off offset:1584
	s_andn2_b64 exec, exec, s[56:57]
	s_cbranch_execz .LBB0_512
.LBB0_499:
	v_mov_b32_e32 v236, 1.0
	v_ashrrev_i32_e32 v2, 8, v145
	v_lshrrev_b32_e32 v3, 2, v145
	v_bfe_u32 v113, v145, 3, 6
	v_bfi_b32 v146, -2, v2, v3
	v_lshlrev_b32_e32 v12, 8, v113
	v_or_b32_e32 v148, v12, v111
	v_lshlrev_b32_e32 v149, 6, v146
	v_lshlrev_b32_e32 v2, 5, v145
	v_lshlrev_b32_e32 v116, 12, v148
	v_and_b32_e32 v124, 0xffffff80, v149
	v_lshlrev_b32_e32 v126, 7, v146
	v_and_b32_e32 v147, 0x60, v2
	v_lshl_add_u64 v[10:11], s[26:27], 0, v[116:117]
	v_ashrrev_i32_e32 v125, 31, v124
	v_ashrrev_i32_e32 v127, 31, v126
	v_lshl_add_u64 v[2:3], v[124:125], 1, v[10:11]
	v_lshl_add_u64 v[10:11], v[126:127], 1, v[10:11]
	s_waitcnt vmcnt(16)
	v_lshlrev_b32_e32 v128, 1, v147
	v_mov_b32_e32 v129, v117
	v_lshl_add_u64 v[10:11], v[10:11], 0, v[128:129]
	v_lshl_add_u64 v[6:7], v[2:3], 0, v[120:121]
	v_lshl_add_u64 v[10:11], v[10:11], 0, v[122:123]
	global_load_dwordx4 v[2:5], v[6:7], off offset:1040
	s_nop 0
	global_load_dwordx4 v[6:9], v[6:7], off offset:1024
	v_or_b32_e32 v150, v12, v160
	global_load_dwordx2 v[134:135], v[10:11], off offset:2048
	v_mov_b32_e32 v152, v117
	v_mov_b32_e32 v151, v117
	s_and_saveexec_b64 s[6:7], vcc
	s_cbranch_execz .LBB0_501
	v_lshl_add_u32 v10, v150, 3, v146
	v_ashrrev_i32_e32 v11, 31, v10
	v_lshlrev_b64 v[10:11], 2, v[10:11]
	v_lshl_add_u64 v[12:13], s[14:15], 0, v[10:11]
	v_lshl_add_u64 v[10:11], s[12:13], 0, v[10:11]
	global_load_dword v151, v[12:13], off
	global_load_dword v152, v[10:11], off

; template <int CTRL> __device__ __forceinline__ float dppf(float v) { return __builtin_bit_cast(float, __builtin_amdgcn_update_dpp(0, __builtin_bit_cast(int, v), CTRL, 0xF, 0xF, true)); }
; template <int MODE>
; __device__ __forceinline__ void gdn_job(const Params& P, float* lw, int head, int rb, int seg) {
;     ...
;         for (int s = 0; s < TBK; ++s) {
;             f32x2 k[8], q[8]; f32x4 v = {0.f, 0.f, 0.f, 0.f};
; #pragma unroll
;             for (int q4 = 0; q4 < 4; ++q4) { const f32x4 x = *(const f32x4*)(sk + s * 128 + jg * 16 + q4 * 4); k[2 * q4] = (f32x2){x.x, x.y}; k[2 * q4 + 1] = (f32x2){x.z, x.w}; }
;             if (MODE == 2) {
; #pragma unroll
;                 for (int q4 = 0; q4 < 4; ++q4) { const f32x4 x = *(const f32x4*)(sq + s * 128 + jg * 16 + q4 * 4); q[2 * q4] = (f32x2){x.x, x.y}; q[2 * q4 + 1] = (f32x2){x.z, x.w}; }
;             }
;             if (MODE != 0) v = *(const f32x4*)(sv + s * 32 + ig * 4);
;             const float al = sal[s], be = sbe[s];
;             float ok = 0.f;
;             float sa[4];
; #pragma unroll
;             for (int ri = 0; ri < 4; ++ri) {
;                 f32x2 a2 = S[ri][0] * k[0], a3 = S[ri][1] * k[1];
; #pragma unroll
;                 for (int jj = 2; jj < 8; jj += 2) { a2 += S[ri][jj] * k[jj]; a3 += S[ri][jj + 1] * k[jj + 1]; }
;                 a2 += a3; sa[ri] = a2.x + a2.y;
;             }
; #pragma unroll
;             for (int ri = 0; ri < 4; ++ri) sa[ri] += dppf<0xB1>(sa[ri]);
; #pragma unroll
;             for (int ri = 0; ri < 4; ++ri) sa[ri] += dppf<0x4E>(sa[ri]);
; #pragma unroll
;             for (int ri = 0; ri < 4; ++ri) sa[ri] += dppf<0x141>(sa[ri]);
; #pragma unroll
;             for (int ri = 0; ri < 4; ++ri) {
;                 const float c = (MODE != 0) ? be * (v[ri] - al * sa[ri]) : -be * al * sa[ri];
; #pragma unroll
;                 for (int jj = 0; jj < 8; ++jj) S[ri][jj] = S[ri][jj] * al + k[jj] * c;
;             }
.LBB0_509:
	ds_read_b128 v[90:93], v115
	ds_read_b128 v[86:89], v115 offset:16
	ds_read_b128 v[82:85], v115 offset:32
	ds_read_b128 v[78:81], v115 offset:48
	v_add_u32_e32 v119, s6, v144
	ds_read2_b64 v[74:77], v116 offset1:4
	ds_read_b128 v[154:157], v119
	ds_read_b128 v[166:169], v119 offset:128
	ds_read_b128 v[94:97], v115 offset:512
	ds_read_b128 v[98:101], v115 offset:528
	ds_read_b128 v[102:105], v115 offset:544
	ds_read_b128 v[106:109], v115 offset:560
	s_waitcnt lgkmcnt(5)
	v_mul_f32_e32 v236, v236, v74
	s_nop 0
	v_readfirstlane_b32 s100, v236
	s_cmp_lt_u32 s100, 0x2b800000
	s_cbranch_scc0 .Lc1_ok_a
	v_pk_mul_f32 v[70:71], v[70:71], v[236:237] op_sel_hi:[1,0]
	v_pk_mul_f32 v[72:73], v[72:73], v[236:237] op_sel_hi:[1,0]
	v_pk_mul_f32 v[66:67], v[66:67], v[236:237] op_sel_hi:[1,0]
	v_pk_mul_f32 v[68:69], v[68:69], v[236:237] op_sel_hi:[1,0]
	v_pk_mul_f32 v[62:63], v[62:63], v[236:237] op_sel_hi:[1,0]
	v_pk_mul_f32 v[64:65], v[64:65], v[236:237] op_sel_hi:[1,0]
	v_pk_mul_f32 v[58:59], v[58:59], v[236:237] op_sel_hi:[1,0]
	v_pk_mul_f32 v[60:61], v[60:61], v[236:237] op_sel_hi:[1,0]
	v_pk_mul_f32 v[54:55], v[54:55], v[236:237] op_sel_hi:[1,0]
	v_pk_mul_f32 v[56:57], v[56:57], v[236:237] op_sel_hi:[1,0]
	v_pk_mul_f32 v[50:51], v[50:51], v[236:237] op_sel_hi:[1,0]
	v_pk_mul_f32 v[52:53], v[52:53], v[236:237] op_sel_hi:[1,0]
	v_pk_mul_f32 v[46:47], v[46:47], v[236:237] op_sel_hi:[1,0]
	v_pk_mul_f32 v[48:49], v[48:49], v[236:237] op_sel_hi:[1,0]
	v_pk_mul_f32 v[42:43], v[42:43], v[236:237] op_sel_hi:[1,0]
	v_pk_mul_f32 v[44:45], v[44:45], v[236:237] op_sel_hi:[1,0]
	v_pk_mul_f32 v[38:39], v[38:39], v[236:237] op_sel_hi:[1,0]
	v_pk_mul_f32 v[40:41], v[40:41], v[236:237] op_sel_hi:[1,0]
	v_pk_mul_f32 v[26:27], v[26:27], v[236:237] op_sel_hi:[1,0]
	v_pk_mul_f32 v[28:29], v[28:29], v[236:237] op_sel_hi:[1,0]
	v_pk_mul_f32 v[18:19], v[18:19], v[236:237] op_sel_hi:[1,0]
	v_pk_mul_f32 v[20:21], v[20:21], v[236:237] op_sel_hi:[1,0]
	v_pk_mul_f32 v[10:11], v[10:11], v[236:237] op_sel_hi:[1,0]
	v_pk_mul_f32 v[12:13], v[12:13], v[236:237] op_sel_hi:[1,0]
	v_pk_mul_f32 v[34:35], v[34:35], v[236:237] op_sel_hi:[1,0]
	v_pk_mul_f32 v[36:37], v[36:37], v[236:237] op_sel_hi:[1,0]
	v_pk_mul_f32 v[30:31], v[30:31], v[236:237] op_sel_hi:[1,0]
	v_pk_mul_f32 v[32:33], v[32:33], v[236:237] op_sel_hi:[1,0]
	v_pk_mul_f32 v[22:23], v[22:23], v[236:237] op_sel_hi:[1,0]
	v_pk_mul_f32 v[24:25], v[24:25], v[236:237] op_sel_hi:[1,0]
	v_pk_mul_f32 v[14:15], v[14:15], v[236:237] op_sel_hi:[1,0]
	v_pk_mul_f32 v[16:17], v[16:17], v[236:237] op_sel_hi:[1,0]
	v_mov_b32_e32 v236, 1.0
.Lc1_ok_a:
	v_rcp_f32_e32 v234, v236
	v_pk_mul_f32 v[170:171], v[70:71], v[90:91]
	v_pk_mul_f32 v[172:173], v[54:55], v[90:91]
	v_pk_mul_f32 v[174:175], v[38:39], v[90:91]
	v_pk_mul_f32 v[176:177], v[34:35], v[90:91]
	v_pk_fma_f32 v[170:171], v[72:73], v[92:93], v[170:171]
	v_pk_fma_f32 v[172:173], v[56:57], v[92:93], v[172:173]
	v_pk_fma_f32 v[174:175], v[40:41], v[92:93], v[174:175]
	v_pk_fma_f32 v[176:177], v[36:37], v[92:93], v[176:177]
	v_pk_fma_f32 v[170:171], v[66:67], v[86:87], v[170:171]
	v_pk_fma_f32 v[172:173], v[50:51], v[86:87], v[172:173]
	v_pk_fma_f32 v[174:175], v[26:27], v[86:87], v[174:175]
	v_pk_fma_f32 v[176:177], v[30:31], v[86:87], v[176:177]
	v_pk_fma_f32 v[170:171], v[68:69], v[88:89], v[170:171]
	v_pk_fma_f32 v[172:173], v[52:53], v[88:89], v[172:173]
	v_pk_fma_f32 v[174:175], v[28:29], v[88:89], v[174:175]
	v_pk_fma_f32 v[176:177], v[32:33], v[88:89], v[176:177]
	v_pk_fma_f32 v[170:171], v[62:63], v[82:83], v[170:171]
	v_pk_fma_f32 v[172:173], v[46:47], v[82:83], v[172:173]
	v_pk_fma_f32 v[174:175], v[18:19], v[82:83], v[174:175]
	v_pk_fma_f32 v[176:177], v[22:23], v[82:83], v[176:177]
	v_pk_fma_f32 v[170:171], v[64:65], v[84:85], v[170:171]
	v_pk_fma_f32 v[172:173], v[48:49], v[84:85], v[172:173]
	v_pk_fma_f32 v[174:175], v[20:21], v[84:85], v[174:175]
	v_pk_fma_f32 v[176:177], v[24:25], v[84:85], v[176:177]
	v_pk_fma_f32 v[170:171], v[58:59], v[78:79], v[170:171]
	v_pk_fma_f32 v[172:173], v[42:43], v[78:79], v[172:173]
	v_pk_fma_f32 v[174:175], v[10:11], v[78:79], v[174:175]
	v_pk_fma_f32 v[176:177], v[14:15], v[78:79], v[176:177]
	v_pk_fma_f32 v[170:171], v[60:61], v[80:81], v[170:171]
	v_pk_fma_f32 v[172:173], v[44:45], v[80:81], v[172:173]
	v_pk_fma_f32 v[174:175], v[12:13], v[80:81], v[174:175]
	v_pk_fma_f32 v[176:177], v[16:17], v[80:81], v[176:177]
	v_add_f32_e32 v170, v170, v171
	v_add_f32_e32 v172, v172, v173
	v_add_f32_e32 v174, v174, v175
	v_add_f32_e32 v176, v176, v177
	v_add_f32_dpp v170, v170, v170 quad_perm:[1,0,3,2] row_mask:0xf bank_mask:0xf bound_ctrl:1
	v_add_f32_dpp v172, v172, v172 quad_perm:[1,0,3,2] row_mask:0xf bank_mask:0xf bound_ctrl:1
	v_add_f32_dpp v174, v174, v174 quad_perm:[1,0,3,2] row_mask:0xf bank_mask:0xf bound_ctrl:1
	v_add_f32_dpp v176, v176, v176 quad_perm:[1,0,3,2] row_mask:0xf bank_mask:0xf bound_ctrl:1
	v_add_f32_dpp v170, v170, v170 quad_perm:[2,3,0,1] row_mask:0xf bank_mask:0xf bound_ctrl:1
	v_add_f32_dpp v172, v172, v172 quad_perm:[2,3,0,1] row_mask:0xf bank_mask:0xf bound_ctrl:1
	v_add_f32_dpp v174, v174, v174 quad_perm:[2,3,0,1] row_mask:0xf bank_mask:0xf bound_ctrl:1
	v_add_f32_dpp v176, v176, v176 quad_perm:[2,3,0,1] row_mask:0xf bank_mask:0xf bound_ctrl:1
	v_add_f32_dpp v170, v170, v170 row_half_mirror row_mask:0xf bank_mask:0xf bound_ctrl:1
	v_add_f32_dpp v172, v172, v172 row_half_mirror row_mask:0xf bank_mask:0xf bound_ctrl:1
	v_add_f32_dpp v174, v174, v174 row_half_mirror row_mask:0xf bank_mask:0xf bound_ctrl:1
	v_add_f32_dpp v176, v176, v176 row_half_mirror row_mask:0xf bank_mask:0xf bound_ctrl:1
	v_mul_f32_e32 v235, v76, v234
; template <int CTRL> __device__ __forceinline__ float dppf(float v) { return __builtin_bit_cast(float, __builtin_amdgcn_update_dpp(0, __builtin_bit_cast(int, v), CTRL, 0xF, 0xF, true)); }
; template <int MODE>
; __device__ __forceinline__ void gdn_job(const Params& P, float* lw, int head, int rb, int seg) {
;     ...
;         for (int s = 0; s < TBK; ++s) {
;             f32x2 k[8], q[8]; f32x4 v = {0.f, 0.f, 0.f, 0.f};
; #pragma unroll
;             for (int q4 = 0; q4 < 4; ++q4) { const f32x4 x = *(const f32x4*)(sk + s * 128 + jg * 16 + q4 * 4); k[2 * q4] = (f32x2){x.x, x.y}; k[2 * q4 + 1] = (f32x2){x.z, x.w}; }
;             if (MODE == 2) {
; #pragma unroll
;                 for (int q4 = 0; q4 < 4; ++q4) { const f32x4 x = *(const f32x4*)(sq + s * 128 + jg * 16 + q4 * 4); q[2 * q4] = (f32x2){x.x, x.y}; q[2 * q4 + 1] = (f32x2){x.z, x.w}; }
;             }
;             if (MODE != 0) v = *(const f32x4*)(sv + s * 32 + ig * 4);
;             const float al = sal[s], be = sbe[s];
;             float ok = 0.f;
;             float sa[4];
; #pragma unroll
;             for (int ri = 0; ri < 4; ++ri) {
;                 f32x2 a2 = S[ri][0] * k[0], a3 = S[ri][1] * k[1];
; #pragma unroll
;                 for (int jj = 2; jj < 8; jj += 2) { a2 += S[ri][jj] * k[jj]; a3 += S[ri][jj + 1] * k[jj + 1]; }
;                 a2 += a3; sa[ri] = a2.x + a2.y;
;             }
; #pragma unroll
;             for (int ri = 0; ri < 4; ++ri) sa[ri] += dppf<0xB1>(sa[ri]);
; #pragma unroll
;             for (int ri = 0; ri < 4; ++ri) sa[ri] += dppf<0x4E>(sa[ri]);
; #pragma unroll
;             for (int ri = 0; ri < 4; ++ri) sa[ri] += dppf<0x141>(sa[ri]);
; #pragma unroll
;             for (int ri = 0; ri < 4; ++ri) {
;                 const float c = (MODE != 0) ? be * (v[ri] - al * sa[ri]) : -be * al * sa[ri];
; #pragma unroll
;                 for (int jj = 0; jj < 8; ++jj) S[ri][jj] = S[ri][jj] * al + k[jj] * c;
;             }
	v_mul_f32_e64 v170, v170, -v76
	v_mul_f32_e64 v172, v172, -v76
	v_mul_f32_e64 v174, v174, -v76
	v_mul_f32_e64 v176, v176, -v76
	v_fmac_f32_e32 v170, v154, v235
	v_fmac_f32_e32 v172, v155, v235
	v_fmac_f32_e32 v174, v156, v235
	v_fmac_f32_e32 v176, v157, v235
	v_pk_fma_f32 v[70:71], v[90:91], v[170:171], v[70:71] op_sel_hi:[1,0,1]
	v_pk_fma_f32 v[72:73], v[92:93], v[170:171], v[72:73] op_sel_hi:[1,0,1]
	v_pk_fma_f32 v[66:67], v[86:87], v[170:171], v[66:67] op_sel_hi:[1,0,1]
	v_pk_fma_f32 v[68:69], v[88:89], v[170:171], v[68:69] op_sel_hi:[1,0,1]
	v_pk_fma_f32 v[62:63], v[82:83], v[170:171], v[62:63] op_sel_hi:[1,0,1]
	v_pk_fma_f32 v[64:65], v[84:85], v[170:171], v[64:65] op_sel_hi:[1,0,1]
	v_pk_fma_f32 v[58:59], v[78:79], v[170:171], v[58:59] op_sel_hi:[1,0,1]
	v_pk_fma_f32 v[60:61], v[80:81], v[170:171], v[60:61] op_sel_hi:[1,0,1]
	v_pk_fma_f32 v[54:55], v[90:91], v[172:173], v[54:55] op_sel_hi:[1,0,1]
	v_pk_fma_f32 v[56:57], v[92:93], v[172:173], v[56:57] op_sel_hi:[1,0,1]
	v_pk_fma_f32 v[50:51], v[86:87], v[172:173], v[50:51] op_sel_hi:[1,0,1]
	v_pk_fma_f32 v[52:53], v[88:89], v[172:173], v[52:53] op_sel_hi:[1,0,1]
	v_pk_fma_f32 v[46:47], v[82:83], v[172:173], v[46:47] op_sel_hi:[1,0,1]
	v_pk_fma_f32 v[48:49], v[84:85], v[172:173], v[48:49] op_sel_hi:[1,0,1]
	v_pk_fma_f32 v[42:43], v[78:79], v[172:173], v[42:43] op_sel_hi:[1,0,1]
	v_pk_fma_f32 v[44:45], v[80:81], v[172:173], v[44:45] op_sel_hi:[1,0,1]
	v_pk_fma_f32 v[38:39], v[90:91], v[174:175], v[38:39] op_sel_hi:[1,0,1]
	v_pk_fma_f32 v[40:41], v[92:93], v[174:175], v[40:41] op_sel_hi:[1,0,1]
	v_pk_fma_f32 v[26:27], v[86:87], v[174:175], v[26:27] op_sel_hi:[1,0,1]
	v_pk_fma_f32 v[28:29], v[88:89], v[174:175], v[28:29] op_sel_hi:[1,0,1]
	v_pk_fma_f32 v[18:19], v[82:83], v[174:175], v[18:19] op_sel_hi:[1,0,1]
	v_pk_fma_f32 v[20:21], v[84:85], v[174:175], v[20:21] op_sel_hi:[1,0,1]
	v_pk_fma_f32 v[10:11], v[78:79], v[174:175], v[10:11] op_sel_hi:[1,0,1]
	v_pk_fma_f32 v[12:13], v[80:81], v[174:175], v[12:13] op_sel_hi:[1,0,1]
	v_pk_fma_f32 v[34:35], v[90:91], v[176:177], v[34:35] op_sel_hi:[1,0,1]
	v_pk_fma_f32 v[36:37], v[92:93], v[176:177], v[36:37] op_sel_hi:[1,0,1]
	v_pk_fma_f32 v[30:31], v[86:87], v[176:177], v[30:31] op_sel_hi:[1,0,1]
	v_pk_fma_f32 v[32:33], v[88:89], v[176:177], v[32:33] op_sel_hi:[1,0,1]
	v_pk_fma_f32 v[22:23], v[82:83], v[176:177], v[22:23] op_sel_hi:[1,0,1]
	v_pk_fma_f32 v[24:25], v[84:85], v[176:177], v[24:25] op_sel_hi:[1,0,1]
	v_pk_fma_f32 v[14:15], v[78:79], v[176:177], v[14:15] op_sel_hi:[1,0,1]
	v_pk_fma_f32 v[16:17], v[80:81], v[176:177], v[16:17] op_sel_hi:[1,0,1]
	s_waitcnt lgkmcnt(0)
	v_mul_f32_e32 v236, v236, v75
	s_nop 0
	v_readfirstlane_b32 s100, v236
	s_cmp_lt_u32 s100, 0x2b800000
	s_cbranch_scc0 .Lc1_ok_b
	v_pk_mul_f32 v[70:71], v[70:71], v[236:237] op_sel_hi:[1,0]
	v_pk_mul_f32 v[72:73], v[72:73], v[236:237] op_sel_hi:[1,0]
	v_pk_mul_f32 v[66:67], v[66:67], v[236:237] op_sel_hi:[1,0]
	v_pk_mul_f32 v[68:69], v[68:69], v[236:237] op_sel_hi:[1,0]
	v_pk_mul_f32 v[62:63], v[62:63], v[236:237] op_sel_hi:[1,0]
	v_pk_mul_f32 v[64:65], v[64:65], v[236:237] op_sel_hi:[1,0]
	v_pk_mul_f32 v[58:59], v[58:59], v[236:237] op_sel_hi:[1,0]
	v_pk_mul_f32 v[60:61], v[60:61], v[236:237] op_sel_hi:[1,0]
	v_pk_mul_f32 v[54:55], v[54:55], v[236:237] op_sel_hi:[1,0]
	v_pk_mul_f32 v[56:57], v[56:57], v[236:237] op_sel_hi:[1,0]
	v_pk_mul_f32 v[50:51], v[50:51], v[236:237] op_sel_hi:[1,0]
	v_pk_mul_f32 v[52:53], v[52:53], v[236:237] op_sel_hi:[1,0]
	v_pk_mul_f32 v[46:47], v[46:47], v[236:237] op_sel_hi:[1,0]
	v_pk_mul_f32 v[48:49], v[48:49], v[236:237] op_sel_hi:[1,0]
	v_pk_mul_f32 v[42:43], v[42:43], v[236:237] op_sel_hi:[1,0]
	v_pk_mul_f32 v[44:45], v[44:45], v[236:237] op_sel_hi:[1,0]
	v_pk_mul_f32 v[38:39], v[38:39], v[236:237] op_sel_hi:[1,0]
	v_pk_mul_f32 v[40:41], v[40:41], v[236:237] op_sel_hi:[1,0]
	v_pk_mul_f32 v[26:27], v[26:27], v[236:237] op_sel_hi:[1,0]
	v_pk_mul_f32 v[28:29], v[28:29], v[236:237] op_sel_hi:[1,0]
	v_pk_mul_f32 v[18:19], v[18:19], v[236:237] op_sel_hi:[1,0]
	v_pk_mul_f32 v[20:21], v[20:21], v[236:237] op_sel_hi:[1,0]
	v_pk_mul_f32 v[10:11], v[10:11], v[236:237] op_sel_hi:[1,0]
	v_pk_mul_f32 v[12:13], v[12:13], v[236:237] op_sel_hi:[1,0]
	v_pk_mul_f32 v[34:35], v[34:35], v[236:237] op_sel_hi:[1,0]
	v_pk_mul_f32 v[36:37], v[36:37], v[236:237] op_sel_hi:[1,0]
	v_pk_mul_f32 v[30:31], v[30:31], v[236:237] op_sel_hi:[1,0]
	v_pk_mul_f32 v[32:33], v[32:33], v[236:237] op_sel_hi:[1,0]
	v_pk_mul_f32 v[22:23], v[22:23], v[236:237] op_sel_hi:[1,0]
	v_pk_mul_f32 v[24:25], v[24:25], v[236:237] op_sel_hi:[1,0]
	v_pk_mul_f32 v[14:15], v[14:15], v[236:237] op_sel_hi:[1,0]
	v_pk_mul_f32 v[16:17], v[16:17], v[236:237] op_sel_hi:[1,0]
	v_mov_b32_e32 v236, 1.0
; template <int CTRL> __device__ __forceinline__ float dppf(float v) { return __builtin_bit_cast(float, __builtin_amdgcn_update_dpp(0, __builtin_bit_cast(int, v), CTRL, 0xF, 0xF, true)); }
; template <int MODE>
; __device__ __forceinline__ void gdn_job(const Params& P, float* lw, int head, int rb, int seg) {
;     ...
;         for (int s = 0; s < TBK; ++s) {
;             f32x2 k[8], q[8]; f32x4 v = {0.f, 0.f, 0.f, 0.f};
; #pragma unroll
;             for (int q4 = 0; q4 < 4; ++q4) { const f32x4 x = *(const f32x4*)(sk + s * 128 + jg * 16 + q4 * 4); k[2 * q4] = (f32x2){x.x, x.y}; k[2 * q4 + 1] = (f32x2){x.z, x.w}; }
;             if (MODE == 2) {
; #pragma unroll
;                 for (int q4 = 0; q4 < 4; ++q4) { const f32x4 x = *(const f32x4*)(sq + s * 128 + jg * 16 + q4 * 4); q[2 * q4] = (f32x2){x.x, x.y}; q[2 * q4 + 1] = (f32x2){x.z, x.w}; }
;             }
;             if (MODE != 0) v = *(const f32x4*)(sv + s * 32 + ig * 4);
;             const float al = sal[s], be = sbe[s];
;             float ok = 0.f;
;             float sa[4];
; #pragma unroll
;             for (int ri = 0; ri < 4; ++ri) {
;                 f32x2 a2 = S[ri][0] * k[0], a3 = S[ri][1] * k[1];
; #pragma unroll
;                 for (int jj = 2; jj < 8; jj += 2) { a2 += S[ri][jj] * k[jj]; a3 += S[ri][jj + 1] * k[jj + 1]; }
;                 a2 += a3; sa[ri] = a2.x + a2.y;
;             }
; #pragma unroll
;             for (int ri = 0; ri < 4; ++ri) sa[ri] += dppf<0xB1>(sa[ri]);
; #pragma unroll
;             for (int ri = 0; ri < 4; ++ri) sa[ri] += dppf<0x4E>(sa[ri]);
; #pragma unroll
;             for (int ri = 0; ri < 4; ++ri) sa[ri] += dppf<0x141>(sa[ri]);
; #pragma unroll
;             for (int ri = 0; ri < 4; ++ri) {
;                 const float c = (MODE != 0) ? be * (v[ri] - al * sa[ri]) : -be * al * sa[ri];
; #pragma unroll
;                 for (int jj = 0; jj < 8; ++jj) S[ri][jj] = S[ri][jj] * al + k[jj] * c;
;             }
.Lc1_ok_b:
	v_rcp_f32_e32 v234, v236
	v_pk_mul_f32 v[170:171], v[70:71], v[94:95]
	v_pk_mul_f32 v[172:173], v[54:55], v[94:95]
	v_pk_mul_f32 v[174:175], v[38:39], v[94:95]
	v_pk_mul_f32 v[176:177], v[34:35], v[94:95]
	v_pk_fma_f32 v[170:171], v[72:73], v[96:97], v[170:171]
	v_pk_fma_f32 v[172:173], v[56:57], v[96:97], v[172:173]
	v_pk_fma_f32 v[174:175], v[40:41], v[96:97], v[174:175]
	v_pk_fma_f32 v[176:177], v[36:37], v[96:97], v[176:177]
	v_pk_fma_f32 v[170:171], v[66:67], v[98:99], v[170:171]
	v_pk_fma_f32 v[172:173], v[50:51], v[98:99], v[172:173]
	v_pk_fma_f32 v[174:175], v[26:27], v[98:99], v[174:175]
	v_pk_fma_f32 v[176:177], v[30:31], v[98:99], v[176:177]
	v_pk_fma_f32 v[170:171], v[68:69], v[100:101], v[170:171]
	v_pk_fma_f32 v[172:173], v[52:53], v[100:101], v[172:173]
	v_pk_fma_f32 v[174:175], v[28:29], v[100:101], v[174:175]
	v_pk_fma_f32 v[176:177], v[32:33], v[100:101], v[176:177]
	v_pk_fma_f32 v[170:171], v[62:63], v[102:103], v[170:171]
	v_pk_fma_f32 v[172:173], v[46:47], v[102:103], v[172:173]
	v_pk_fma_f32 v[174:175], v[18:19], v[102:103], v[174:175]
	v_pk_fma_f32 v[176:177], v[22:23], v[102:103], v[176:177]
	v_pk_fma_f32 v[170:171], v[64:65], v[104:105], v[170:171]
	v_pk_fma_f32 v[172:173], v[48:49], v[104:105], v[172:173]
	v_pk_fma_f32 v[174:175], v[20:21], v[104:105], v[174:175]
	v_pk_fma_f32 v[176:177], v[24:25], v[104:105], v[176:177]
	v_pk_fma_f32 v[170:171], v[58:59], v[106:107], v[170:171]
	v_pk_fma_f32 v[172:173], v[42:43], v[106:107], v[172:173]
	v_pk_fma_f32 v[174:175], v[10:11], v[106:107], v[174:175]
	v_pk_fma_f32 v[176:177], v[14:15], v[106:107], v[176:177]
	v_pk_fma_f32 v[170:171], v[60:61], v[108:109], v[170:171]
	v_pk_fma_f32 v[172:173], v[44:45], v[108:109], v[172:173]
	v_pk_fma_f32 v[174:175], v[12:13], v[108:109], v[174:175]
	v_pk_fma_f32 v[176:177], v[16:17], v[108:109], v[176:177]
	v_add_f32_e32 v170, v170, v171
	v_add_f32_e32 v172, v172, v173
	v_add_f32_e32 v174, v174, v175
	v_add_f32_e32 v176, v176, v177
	v_add_f32_dpp v170, v170, v170 quad_perm:[1,0,3,2] row_mask:0xf bank_mask:0xf bound_ctrl:1
	v_add_f32_dpp v172, v172, v172 quad_perm:[1,0,3,2] row_mask:0xf bank_mask:0xf bound_ctrl:1
	v_add_f32_dpp v174, v174, v174 quad_perm:[1,0,3,2] row_mask:0xf bank_mask:0xf bound_ctrl:1
	v_add_f32_dpp v176, v176, v176 quad_perm:[1,0,3,2] row_mask:0xf bank_mask:0xf bound_ctrl:1
	v_add_f32_dpp v170, v170, v170 quad_perm:[2,3,0,1] row_mask:0xf bank_mask:0xf bound_ctrl:1
	v_add_f32_dpp v172, v172, v172 quad_perm:[2,3,0,1] row_mask:0xf bank_mask:0xf bound_ctrl:1
	v_add_f32_dpp v174, v174, v174 quad_perm:[2,3,0,1] row_mask:0xf bank_mask:0xf bound_ctrl:1
	v_add_f32_dpp v176, v176, v176 quad_perm:[2,3,0,1] row_mask:0xf bank_mask:0xf bound_ctrl:1
	v_add_f32_dpp v170, v170, v170 row_half_mirror row_mask:0xf bank_mask:0xf bound_ctrl:1
	v_add_f32_dpp v172, v172, v172 row_half_mirror row_mask:0xf bank_mask:0xf bound_ctrl:1
	v_add_f32_dpp v174, v174, v174 row_half_mirror row_mask:0xf bank_mask:0xf bound_ctrl:1
	v_add_f32_dpp v176, v176, v176 row_half_mirror row_mask:0xf bank_mask:0xf bound_ctrl:1
	v_mul_f32_e32 v235, v77, v234
	v_mul_f32_e64 v170, v170, -v77
	v_mul_f32_e64 v172, v172, -v77
	v_mul_f32_e64 v174, v174, -v77
	v_mul_f32_e64 v176, v176, -v77
	v_fmac_f32_e32 v170, v166, v235
	v_fmac_f32_e32 v172, v167, v235
	v_fmac_f32_e32 v174, v168, v235
	v_fmac_f32_e32 v176, v169, v235
	v_pk_fma_f32 v[70:71], v[94:95], v[170:171], v[70:71] op_sel_hi:[1,0,1]
	v_pk_fma_f32 v[72:73], v[96:97], v[170:171], v[72:73] op_sel_hi:[1,0,1]
	v_pk_fma_f32 v[66:67], v[98:99], v[170:171], v[66:67] op_sel_hi:[1,0,1]
	v_pk_fma_f32 v[68:69], v[100:101], v[170:171], v[68:69] op_sel_hi:[1,0,1]
	v_pk_fma_f32 v[62:63], v[102:103], v[170:171], v[62:63] op_sel_hi:[1,0,1]
	v_pk_fma_f32 v[64:65], v[104:105], v[170:171], v[64:65] op_sel_hi:[1,0,1]
	v_pk_fma_f32 v[58:59], v[106:107], v[170:171], v[58:59] op_sel_hi:[1,0,1]
	v_pk_fma_f32 v[60:61], v[108:109], v[170:171], v[60:61] op_sel_hi:[1,0,1]
	v_pk_fma_f32 v[54:55], v[94:95], v[172:173], v[54:55] op_sel_hi:[1,0,1]
	v_pk_fma_f32 v[56:57], v[96:97], v[172:173], v[56:57] op_sel_hi:[1,0,1]
	v_pk_fma_f32 v[50:51], v[98:99], v[172:173], v[50:51] op_sel_hi:[1,0,1]
	v_pk_fma_f32 v[52:53], v[100:101], v[172:173], v[52:53] op_sel_hi:[1,0,1]
	v_pk_fma_f32 v[46:47], v[102:103], v[172:173], v[46:47] op_sel_hi:[1,0,1]
	v_pk_fma_f32 v[48:49], v[104:105], v[172:173], v[48:49] op_sel_hi:[1,0,1]
	v_pk_fma_f32 v[42:43], v[106:107], v[172:173], v[42:43] op_sel_hi:[1,0,1]
	v_pk_fma_f32 v[44:45], v[108:109], v[172:173], v[44:45] op_sel_hi:[1,0,1]
	v_pk_fma_f32 v[38:39], v[94:95], v[174:175], v[38:39] op_sel_hi:[1,0,1]
	v_pk_fma_f32 v[40:41], v[96:97], v[174:175], v[40:41] op_sel_hi:[1,0,1]
	v_pk_fma_f32 v[26:27], v[98:99], v[174:175], v[26:27] op_sel_hi:[1,0,1]
	v_pk_fma_f32 v[28:29], v[100:101], v[174:175], v[28:29] op_sel_hi:[1,0,1]
	v_pk_fma_f32 v[18:19], v[102:103], v[174:175], v[18:19] op_sel_hi:[1,0,1]
	v_pk_fma_f32 v[20:21], v[104:105], v[174:175], v[20:21] op_sel_hi:[1,0,1]
	v_pk_fma_f32 v[10:11], v[106:107], v[174:175], v[10:11] op_sel_hi:[1,0,1]
	v_pk_fma_f32 v[12:13], v[108:109], v[174:175], v[12:13] op_sel_hi:[1,0,1]
	v_pk_fma_f32 v[34:35], v[94:95], v[176:177], v[34:35] op_sel_hi:[1,0,1]
	v_pk_fma_f32 v[36:37], v[96:97], v[176:177], v[36:37] op_sel_hi:[1,0,1]
	v_pk_fma_f32 v[30:31], v[98:99], v[176:177], v[30:31] op_sel_hi:[1,0,1]
	v_pk_fma_f32 v[32:33], v[100:101], v[176:177], v[32:33] op_sel_hi:[1,0,1]
	v_pk_fma_f32 v[22:23], v[102:103], v[176:177], v[22:23] op_sel_hi:[1,0,1]
	v_pk_fma_f32 v[24:25], v[104:105], v[176:177], v[24:25] op_sel_hi:[1,0,1]
	v_pk_fma_f32 v[14:15], v[106:107], v[176:177], v[14:15] op_sel_hi:[1,0,1]
	v_pk_fma_f32 v[16:17], v[108:109], v[176:177], v[16:17] op_sel_hi:[1,0,1]
	s_addk_i32 s6, 0x100
	v_add_u32_e32 v116, 8, v116
	v_add_u32_e32 v115, 0x400, v115
	s_cmpk_eq_i32 s6, 0x400
	s_cbranch_scc0 .LBB0_509
	s_cmp_eq_u32 s41, 32
	s_cbranch_scc1 .LBB0_498
	s_mov_b32 s43, s41
	s_branch .LBB0_502

; __global__ void __launch_bounds__(512, 2) fwd_megakernel(Params P) {
;     extern __shared__ __attribute__((aligned(16))) unsigned char smem[];
	.amdhsa_kernel _Z14fwd_megakernel6Params
		.amdhsa_group_segment_fixed_size 0
		.amdhsa_private_segment_fixed_size 0
		.amdhsa_kernarg_size 560
		.amdhsa_user_sgpr_count 2
		.amdhsa_user_sgpr_dispatch_ptr 0
		.amdhsa_user_sgpr_queue_ptr 0
		.amdhsa_user_sgpr_kernarg_segment_ptr 1
		.amdhsa_user_sgpr_dispatch_id 0
		.amdhsa_user_sgpr_kernarg_preload_length 0
		.amdhsa_user_sgpr_kernarg_preload_offset 0
		.amdhsa_user_sgpr_private_segment_size 0
		.amdhsa_uses_dynamic_stack 0
		.amdhsa_enable_private_segment 0
		.amdhsa_system_sgpr_workgroup_id_x 1
		.amdhsa_system_sgpr_workgroup_id_y 0
		.amdhsa_system_sgpr_workgroup_id_z 0
		.amdhsa_system_sgpr_workgroup_info 0
		.amdhsa_system_vgpr_workitem_id 2
		.amdhsa_next_free_vgpr 239
		.amdhsa_next_free_sgpr 102
		.amdhsa_accum_offset 240
		.amdhsa_reserve_vcc 1
		.amdhsa_float_round_mode_32 0
		.amdhsa_float_round_mode_16_64 0
		.amdhsa_float_denorm_mode_32 3
		.amdhsa_float_denorm_mode_16_64 3
		.amdhsa_dx10_clamp 1
		.amdhsa_ieee_mode 1
		.amdhsa_fp16_overflow 0
		.amdhsa_tg_split 0
		.amdhsa_exception_fp_ieee_invalid_op 0
		.amdhsa_exception_fp_denorm_src 0
		.amdhsa_exception_fp_ieee_div_zero 0
		.amdhsa_exception_fp_ieee_overflow 0
		.amdhsa_exception_fp_ieee_underflow 0
		.amdhsa_exception_fp_ieee_inexact 0
		.amdhsa_exception_int_div_zero 0
	.end_amdhsa_kernel

; __global__ void __launch_bounds__(512, 2) fwd_megakernel(Params P) {
;     extern __shared__ __attribute__((aligned(16))) unsigned char smem[];
amdhsa.kernels:
  - .agpr_count:     0
    .args:
      - .offset:         0
        .size:           304
        .value_kind:     by_value
      - .offset:         304
        .size:           4
        .value_kind:     hidden_block_count_x
      - .offset:         308
        .size:           4
        .value_kind:     hidden_block_count_y
      - .offset:         312
        .size:           4
        .value_kind:     hidden_block_count_z
      - .offset:         316
        .size:           2
        .value_kind:     hidden_group_size_x
      - .offset:         318
        .size:           2
        .value_kind:     hidden_group_size_y
      - .offset:         320
        .size:           2
        .value_kind:     hidden_group_size_z
      - .offset:         322
        .size:           2
        .value_kind:     hidden_remainder_x
      - .offset:         324
        .size:           2
        .value_kind:     hidden_remainder_y
      - .offset:         326
        .size:           2
        .value_kind:     hidden_remainder_z
      - .offset:         344
        .size:           8
        .value_kind:     hidden_global_offset_x
      - .offset:         352
        .size:           8
        .value_kind:     hidden_global_offset_y
      - .offset:         360
        .size:           8
        .value_kind:     hidden_global_offset_z
      - .offset:         368
        .size:           2
        .value_kind:     hidden_grid_dims
      - .offset:         392
        .size:           8
        .value_kind:     hidden_multigrid_sync_arg
      - .offset:         424
        .size:           4
        .value_kind:     hidden_dynamic_lds_size
    .group_segment_fixed_size: 0
    .kernarg_segment_align: 8
    .kernarg_segment_size: 560
    .language:       OpenCL C
    .language_version:
      - 2
      - 0
    .max_flat_workgroup_size: 512
    .name:           _Z14fwd_megakernel6Params
    .private_segment_fixed_size: 0
    .sgpr_count:     108
    .sgpr_spill_count: 2
    .symbol:         _Z14fwd_megakernel6Params.kd
    .uniform_work_group_size: 1
    .uses_dynamic_stack: false
    .vgpr_count:     239
    .vgpr_spill_count: 0
    .wavefront_size: 64
